# P2: lines of p for the P16 block touched during the conv mixer (L2 warm-up)
# speedup vs baseline: 1.0028x; 1.0028x over previous
; #define LAS __attribute__((address_space(3)))
; __global__ void __launch_bounds__(NWAVES * 64, 2) fwd_kernel(Args args) {
;     ...
;                 const int t0 = cu * 64; const int tb = t0 & (SEQ - 1);
;                 { u32x4 wv[4], uv[12];
;                   if (first) {
; #pragma unroll
;                       for (int q = 0; q < 4; ++q) wv[q] = *((const u32x4*)CW16 + tid + 512 * q);
;                   }
; #pragma unroll
;                   for (int q = 0; q < 12; ++q) { const int i = tid + 512 * q; const int rr = i >> 6, ch = i & 63;
;                       const bool ok = i < 94 * 64 && tb - 30 + rr >= 0;
;                       const u32x4 ld = *(const u32x4*)(Ub + (ok ? (size_t)(t0 - 30 + rr) * CONV_CH + ch * 8 : (size_t)0));
;                       uv[q] = ok ? ld : (u32x4){0u, 0u, 0u, 0u}; }
;                   __syncthreads();
;                   if (first) {
; #pragma unroll
;                       for (int q = 0; q < 4; ++q) *((LAS u32x4*)wt + tid + 512 * q) = wv[q];
;                       ut[94 * CONV_CH + tid] = (f16_t)0.f;
;                   }
; #pragma unroll
;                   for (int q = 0; q < 12; ++q) { const int i = tid + 512 * q; if (i < 94 * 64) *((LAS u32x4*)ut + i) = uv[q]; } }
;                 first = false;
;                 __syncthreads();
;                 float acc[8][8];
; #pragma unroll
;                 for (int i = 0; i < 8; ++i)
; #pragma unroll
;                     for (int e = 0; e < 8; ++e) acc[i][e] = 0.f;
;                 const LAS f16_t* ub = ut + (wave * 8) * CONV_CH + c0;
;                 const LAS f16_t* wb = wt + c0;
;                 f16x8 win[15];
; #pragma unroll
;                 for (int i = 0; i < 7; ++i) win[8 + i] = *(const LAS f16x8*)(ub + i * CONV_CH);
;     ...
;         { const size_t n8 = (size_t)M * PLE / 8, stride = (size_t)nwk;
;           for (size_t i = (size_t)wk; i < n8; i += 4 * stride) {
;             f32x4 a[4], b[4];
; #pragma unroll
;             for (int q = 0; q < 4; ++q) { const size_t ii = (i + q * stride < n8) ? i + q * stride : n8 - 1; a[q] = __builtin_nontemporal_load((const f32x4*)p + 2 * ii); b[q] = __builtin_nontemporal_load((const f32x4*)p + 2 * ii + 1); }
.LBB0_643:
	s_waitcnt vmcnt(6)
	ds_write_b128 v201, v[22:25]
	ds_write_b128 v201, v[18:21] offset:8192
	ds_write_b128 v201, v[30:33] offset:16384
	ds_write_b128 v201, v[26:29] offset:24576
	s_waitcnt vmcnt(5)
	ds_write_b128 v201, v[34:37] offset:32768
	s_waitcnt vmcnt(4)
	ds_write_b128 v201, v[38:41] offset:40960
	s_waitcnt vmcnt(3)
	ds_write_b128 v201, v[46:49] offset:49152
	s_waitcnt vmcnt(2)
	ds_write_b128 v201, v[50:53] offset:57344
	s_waitcnt vmcnt(1)
	ds_write_b128 v202, v[58:61]
	s_waitcnt vmcnt(0)
	v_lshl_add_u32 v249, s85, 9, v0
	v_lshlrev_b32_e32 v249, 5, v249
	global_load_dword v250, v249, s[38:39]
	s_add_u32 s98, s38, 0x400000
	s_addc_u32 s99, s39, 0
	global_load_dword v251, v249, s[98:99]
	s_add_u32 s98, s38, 0x800000
	s_addc_u32 s99, s39, 0
	global_load_dword v252, v249, s[98:99]
	s_add_u32 s98, s38, 0xc00000
	s_addc_u32 s99, s39, 0
	global_load_dword v253, v249, s[98:99]
	ds_write_b128 v203, v[62:65]
	s_and_saveexec_b64 s[0:1], s[2:3]
	ds_write_b128 v204, v[54:57]
	s_or_b64 exec, exec, s[0:1]
	s_and_saveexec_b64 s[0:1], s[4:5]
	ds_write_b128 v205, v[42:45]
	s_or_b64 exec, exec, s[0:1]
	s_waitcnt lgkmcnt(0)
	s_barrier
	ds_read_b128 v[42:45], v206
	ds_read_b128 v[38:41], v206 offset:1024
	ds_read_b128 v[30:33], v206 offset:2048
	ds_read_b128 v[18:21], v206 offset:3072
	ds_read_b128 v[22:25], v206 offset:4096
	ds_read_b128 v[26:29], v206 offset:5120
	ds_read_b128 v[34:37], v206 offset:6144
	v_mov_b32_e32 v174, 0
	s_mov_b32 s0, -8
	v_mov_b32_e32 v208, v98
	v_mov_b32_e32 v175, v174
	v_mov_b32_e32 v176, v174
	v_mov_b32_e32 v177, v174
	v_mov_b32_e32 v178, v174
	v_mov_b32_e32 v179, v174
	v_mov_b32_e32 v180, v174
	v_mov_b32_e32 v181, v174
	v_mov_b32_e32 v166, v174
	v_mov_b32_e32 v167, v174
	v_mov_b32_e32 v168, v174
	v_mov_b32_e32 v169, v174
	v_mov_b32_e32 v170, v174
	v_mov_b32_e32 v171, v174
	v_mov_b32_e32 v172, v174
	v_mov_b32_e32 v173, v174
	v_mov_b32_e32 v164, v174
	v_mov_b32_e32 v165, v174
	v_mov_b32_e32 v162, v174
	v_mov_b32_e32 v163, v174
	v_mov_b32_e32 v160, v174
	v_mov_b32_e32 v161, v174
	v_mov_b32_e32 v158, v174
	v_mov_b32_e32 v159, v174
	v_mov_b32_e32 v150, v174
	v_mov_b32_e32 v151, v174
	v_mov_b32_e32 v152, v174
	v_mov_b32_e32 v153, v174
	v_mov_b32_e32 v154, v174
	v_mov_b32_e32 v155, v174
	v_mov_b32_e32 v156, v174
	v_mov_b32_e32 v157, v174
	v_mov_b32_e32 v142, v174
	v_mov_b32_e32 v143, v174
	v_mov_b32_e32 v144, v174
	v_mov_b32_e32 v145, v174
	v_mov_b32_e32 v146, v174
	v_mov_b32_e32 v147, v174
	v_mov_b32_e32 v148, v174
	v_mov_b32_e32 v149, v174
	v_mov_b32_e32 v134, v174
	v_mov_b32_e32 v135, v174
	v_mov_b32_e32 v136, v174
	v_mov_b32_e32 v137, v174
	v_mov_b32_e32 v138, v174
	v_mov_b32_e32 v139, v174
	v_mov_b32_e32 v140, v174
	v_mov_b32_e32 v141, v174
	v_mov_b32_e32 v126, v174
	v_mov_b32_e32 v127, v174
	v_mov_b32_e32 v128, v174
	v_mov_b32_e32 v129, v174
	v_mov_b32_e32 v130, v174
	v_mov_b32_e32 v131, v174
	v_mov_b32_e32 v132, v174
	v_mov_b32_e32 v133, v174
	v_mov_b32_e32 v118, v174
	v_mov_b32_e32 v119, v174
	v_mov_b32_e32 v120, v174
	v_mov_b32_e32 v121, v174
	v_mov_b32_e32 v122, v174
	v_mov_b32_e32 v123, v174
	v_mov_b32_e32 v124, v174
	v_mov_b32_e32 v125, v174

; __global__ void __launch_bounds__(NWAVES * 64, 2) fwd_kernel(Args args) {
;     extern __shared__ __attribute__((aligned(16))) unsigned char lds_raw[];
	.amdhsa_kernel _Z10fwd_kernel4Args
		.amdhsa_group_segment_fixed_size 0
		.amdhsa_private_segment_fixed_size 0
		.amdhsa_kernarg_size 424
		.amdhsa_user_sgpr_count 2
		.amdhsa_user_sgpr_dispatch_ptr 0
		.amdhsa_user_sgpr_queue_ptr 0
		.amdhsa_user_sgpr_kernarg_segment_ptr 1
		.amdhsa_user_sgpr_dispatch_id 0
		.amdhsa_user_sgpr_kernarg_preload_length 0
		.amdhsa_user_sgpr_kernarg_preload_offset 0
		.amdhsa_user_sgpr_private_segment_size 0
		.amdhsa_uses_dynamic_stack 0
		.amdhsa_enable_private_segment 0
		.amdhsa_system_sgpr_workgroup_id_x 1
		.amdhsa_system_sgpr_workgroup_id_y 0
		.amdhsa_system_sgpr_workgroup_id_z 0
		.amdhsa_system_sgpr_workgroup_info 0
		.amdhsa_system_vgpr_workitem_id 0
		.amdhsa_next_free_vgpr 255
		.amdhsa_next_free_sgpr 102
		.amdhsa_accum_offset 256
		.amdhsa_reserve_vcc 1
		.amdhsa_float_round_mode_32 0
		.amdhsa_float_round_mode_16_64 0
		.amdhsa_float_denorm_mode_32 3
		.amdhsa_float_denorm_mode_16_64 3
		.amdhsa_dx10_clamp 1
		.amdhsa_ieee_mode 1
		.amdhsa_fp16_overflow 0
		.amdhsa_tg_split 0
		.amdhsa_exception_fp_ieee_invalid_op 0
		.amdhsa_exception_fp_denorm_src 0
		.amdhsa_exception_fp_ieee_div_zero 0
		.amdhsa_exception_fp_ieee_overflow 0
		.amdhsa_exception_fp_ieee_underflow 0
		.amdhsa_exception_fp_ieee_inexact 0
		.amdhsa_exception_int_div_zero 0
	.end_amdhsa_kernel

; __global__ void __launch_bounds__(NWAVES * 64, 2) fwd_kernel(Args args) {
;     extern __shared__ __attribute__((aligned(16))) unsigned char lds_raw[];
amdhsa.kernels:
  - .agpr_count:     0
    .args:
      - .offset:         0
        .size:           168
        .value_kind:     by_value
      - .offset:         168
        .size:           4
        .value_kind:     hidden_block_count_x
      - .offset:         172
        .size:           4
        .value_kind:     hidden_block_count_y
      - .offset:         176
        .size:           4
        .value_kind:     hidden_block_count_z
      - .offset:         180
        .size:           2
        .value_kind:     hidden_group_size_x
      - .offset:         182
        .size:           2
        .value_kind:     hidden_group_size_y
      - .offset:         184
        .size:           2
        .value_kind:     hidden_group_size_z
      - .offset:         186
        .size:           2
        .value_kind:     hidden_remainder_x
      - .offset:         188
        .size:           2
        .value_kind:     hidden_remainder_y
      - .offset:         190
        .size:           2
        .value_kind:     hidden_remainder_z
      - .offset:         208
        .size:           8
        .value_kind:     hidden_global_offset_x
      - .offset:         216
        .size:           8
        .value_kind:     hidden_global_offset_y
      - .offset:         224
        .size:           8
        .value_kind:     hidden_global_offset_z
      - .offset:         232
        .size:           2
        .value_kind:     hidden_grid_dims
      - .offset:         288
        .size:           4
        .value_kind:     hidden_dynamic_lds_size
    .group_segment_fixed_size: 0
    .kernarg_segment_align: 8
    .kernarg_segment_size: 424
    .language:       OpenCL C
    .language_version:
      - 2
      - 0
    .max_flat_workgroup_size: 512
    .name:           _Z10fwd_kernel4Args
    .private_segment_fixed_size: 0
    .sgpr_count:     108
    .sgpr_spill_count: 76
    .symbol:         _Z10fwd_kernel4Args.kd
    .uniform_work_group_size: 1
    .uses_dynamic_stack: false
    .vgpr_count:     255
    .vgpr_spill_count: 0
    .wavefront_size: 64
